# P0 weight copies rewritten: 8x4 block per thread-iteration with 16-byte loads (4x the bytes in flight), bit-identical outputs
# baseline (speedup 1.0000x reference)
.LBB0_19:
	s_or_b64 exec, exec, s[2:3]
	v_readfirstlane_b32 s16, v1
	s_lshl_b32 s2, s86, 9
	s_and_b32 s29, s16, 0xffffffc0
	s_mov_b64 s[10:11], s[88:89]
	v_writelane_b32 v253, s2, 0
	s_add_i32 s2, s29, s2
	v_mbcnt_lo_u32_b32 v0, -1, 0
	v_mbcnt_hi_u32_b32 v0, -1, v0

	v_add_u32_e32 v4, s2, v0
	s_load_dwordx2 s[2:3], s[10:11], 0x88
	s_load_dwordx2 s[6:7], s[10:11], 0xa8
	s_lshl_b32 s85, s56, 9


	s_load_dwordx2 s[10:11], s[10:11], 0x20
	s_mov_b32 s18, 0x42000
	s_mov_b32 s20, 0x41fff
	s_mov_b64 s[14:15], 0x8400
	s_mov_b64 s[22:23], 0x1000
	s_movk_i32 s19, 0x1000
	v_mov_b32_e32 v5, v4
	s_mov_b64 s[12:13], 0
	v_cmp_gt_i32_e32 vcc, s18, v5
	s_and_saveexec_b64 s[8:9], vcc
	s_cbranch_execz .Lw1_done
	s_waitcnt lgkmcnt(0)
.Lw1_loop:
	v_lshrrev_b32_e32 v0, 6, v5
	v_mul_u32_u24_e32 v1, 0x7c2, v0
	v_lshrrev_b32_e32 v1, 16, v1
	v_mul_u32_u24_e32 v0, 0x840, v1
	v_sub_u32_e32 v0, v5, v0
	v_lshlrev_b32_e32 v0, 2, v0
	v_cmp_gt_u32_e32 vcc, s19, v0
	v_bfe_u32 v2, v0, 7, 1
	v_bfe_u32 v3, v0, 2, 1
	v_lshl_add_u32 v2, v2, 1, v3
	v_lshrrev_b32_e32 v3, 8, v0
	v_lshlrev_b32_e32 v3, 6, v3
	v_lshl_add_u32 v2, v2, 10, v3
	v_bfe_u32 v3, v0, 3, 4
	v_lshl_add_u32 v2, v3, 2, v2
	v_cndmask_b32_e32 v2, v0, v2, vcc
	v_mul_u32_u24_e32 v3, 0x42000, v1
	v_lshl_add_u32 v6, v2, 2, v3
	v_mov_b32_e32 v7, 0
	v_lshl_add_u64 v[6:7], s[10:11], 0, v[6:7]
	global_load_dwordx4 v[8:11], v[6:7], off
	v_lshl_add_u64 v[6:7], v[6:7], 0, s[14:15]
	global_load_dwordx4 v[12:15], v[6:7], off
	v_lshl_add_u64 v[6:7], v[6:7], 0, s[14:15]
	global_load_dwordx4 v[16:19], v[6:7], off
	v_lshl_add_u64 v[6:7], v[6:7], 0, s[14:15]
	global_load_dwordx4 v[20:23], v[6:7], off
	v_lshl_add_u64 v[6:7], v[6:7], 0, s[14:15]
	global_load_dwordx4 v[24:27], v[6:7], off
	v_lshl_add_u64 v[6:7], v[6:7], 0, s[14:15]
	global_load_dwordx4 v[28:31], v[6:7], off
	v_lshl_add_u64 v[6:7], v[6:7], 0, s[14:15]
	global_load_dwordx4 v[32:35], v[6:7], off
	v_lshl_add_u64 v[6:7], v[6:7], 0, s[14:15]
	global_load_dwordx4 v[36:39], v[6:7], off
	v_lshlrev_b32_e32 v40, 11, v0
	v_lshl_add_u32 v40, v1, 4, v40
	v_mov_b32_e32 v41, 0
	v_lshl_add_u64 v[40:41], s[6:7], 0, v[40:41]
	v_lshl_add_u64 v[42:43], v[40:41], 0, s[22:23]
	v_add_u32_e32 v5, s85, v5
	v_cmp_lt_i32_e32 vcc, s20, v5
	s_waitcnt vmcnt(0)
	v_cvt_pk_bf16_f32 v44, v8, v12
	v_cvt_pk_bf16_f32 v45, v16, v20
	v_cvt_pk_bf16_f32 v46, v24, v28
	v_cvt_pk_bf16_f32 v47, v32, v36
	v_cvt_pk_bf16_f32 v48, v9, v13
	v_cvt_pk_bf16_f32 v49, v17, v21
	v_cvt_pk_bf16_f32 v50, v25, v29
	v_cvt_pk_bf16_f32 v51, v33, v37
	v_cvt_pk_bf16_f32 v52, v10, v14
	v_cvt_pk_bf16_f32 v53, v18, v22
	v_cvt_pk_bf16_f32 v54, v26, v30
	v_cvt_pk_bf16_f32 v55, v34, v38
	v_cvt_pk_bf16_f32 v56, v11, v15
	v_cvt_pk_bf16_f32 v57, v19, v23
	v_cvt_pk_bf16_f32 v58, v27, v31
	v_cvt_pk_bf16_f32 v59, v35, v39
	s_or_b64 s[12:13], vcc, s[12:13]
	global_store_dwordx4 v[40:41], v[44:47], off
	global_store_dwordx4 v[40:41], v[48:51], off offset:2048
	global_store_dwordx4 v[42:43], v[52:55], off
	global_store_dwordx4 v[42:43], v[56:59], off offset:2048
	s_andn2_b64 exec, exec, s[12:13]
	s_cbranch_execnz .Lw1_loop
.Lw1_done:
	s_or_b64 exec, exec, s[8:9]
	s_mov_b32 s18, 0x10000
	s_mov_b32 s20, 0xffff
	v_mov_b32_e32 v5, v4
	s_mov_b64 s[12:13], 0
	v_cmp_gt_i32_e32 vcc, s18, v5
	s_and_saveexec_b64 s[8:9], vcc
	s_cbranch_execz .Lw2_done
	s_waitcnt lgkmcnt(0)
	s_add_u32 s6, s6, 0x1080000
	s_addc_u32 s7, s7, 0
.Lw2_loop:
	v_and_b32_e32 v0, 0xff, v5
	v_lshlrev_b32_e32 v0, 2, v0
	v_lshrrev_b32_e32 v1, 8, v5
	v_lshlrev_b32_e32 v6, 15, v1
	v_lshl_add_u32 v6, v0, 2, v6
	v_mov_b32_e32 v7, 0
	v_lshl_add_u64 v[6:7], s[2:3], 0, v[6:7]
	global_load_dwordx4 v[8:11], v[6:7], off
	v_lshl_add_u64 v[6:7], v[6:7], 0, s[22:23]
	global_load_dwordx4 v[12:15], v[6:7], off
	v_lshl_add_u64 v[6:7], v[6:7], 0, s[22:23]
	global_load_dwordx4 v[16:19], v[6:7], off
	v_lshl_add_u64 v[6:7], v[6:7], 0, s[22:23]
	global_load_dwordx4 v[20:23], v[6:7], off
	v_lshl_add_u64 v[6:7], v[6:7], 0, s[22:23]
	global_load_dwordx4 v[24:27], v[6:7], off
	v_lshl_add_u64 v[6:7], v[6:7], 0, s[22:23]
	global_load_dwordx4 v[28:31], v[6:7], off
	v_lshl_add_u64 v[6:7], v[6:7], 0, s[22:23]
	global_load_dwordx4 v[32:35], v[6:7], off
	v_lshl_add_u64 v[6:7], v[6:7], 0, s[22:23]
	global_load_dwordx4 v[36:39], v[6:7], off
	v_lshlrev_b32_e32 v40, 12, v0
	v_lshl_add_u32 v40, v1, 4, v40
	v_mov_b32_e32 v41, 0
	v_lshl_add_u64 v[40:41], s[6:7], 0, v[40:41]
	v_lshl_add_u64 v[42:43], v[40:41], 0, s[22:23]
	v_lshl_add_u64 v[60:61], v[42:43], 0, s[22:23]
	v_lshl_add_u64 v[62:63], v[60:61], 0, s[22:23]
	v_add_u32_e32 v5, s85, v5
	v_cmp_lt_i32_e32 vcc, s20, v5
	s_waitcnt vmcnt(0)
	v_cvt_pk_bf16_f32 v44, v8, v12
	v_cvt_pk_bf16_f32 v45, v16, v20
	v_cvt_pk_bf16_f32 v46, v24, v28
	v_cvt_pk_bf16_f32 v47, v32, v36
	v_cvt_pk_bf16_f32 v48, v9, v13
	v_cvt_pk_bf16_f32 v49, v17, v21
	v_cvt_pk_bf16_f32 v50, v25, v29
	v_cvt_pk_bf16_f32 v51, v33, v37
	v_cvt_pk_bf16_f32 v52, v10, v14
	v_cvt_pk_bf16_f32 v53, v18, v22
	v_cvt_pk_bf16_f32 v54, v26, v30
	v_cvt_pk_bf16_f32 v55, v34, v38
	v_cvt_pk_bf16_f32 v56, v11, v15
	v_cvt_pk_bf16_f32 v57, v19, v23
	v_cvt_pk_bf16_f32 v58, v27, v31
	v_cvt_pk_bf16_f32 v59, v35, v39
	s_or_b64 s[12:13], vcc, s[12:13]
	global_store_dwordx4 v[40:41], v[44:47], off
	global_store_dwordx4 v[42:43], v[48:51], off
	global_store_dwordx4 v[60:61], v[52:55], off
	global_store_dwordx4 v[62:63], v[56:59], off
	s_andn2_b64 exec, exec, s[12:13]
	s_cbranch_execnz .Lw2_loop
